# add 12us XCD-group stagger at P4 start (residues 4-7) to desynchronise HBM-bound epilogue bursts
# speedup vs baseline: 1.0056x; 1.0039x over previous
.LBB0_694:
	s_cmp_eq_u32 s99, 0
	s_cbranch_scc1 .Lstag4_done
	s_bitcmp1_b32 s2, 2
	s_cbranch_scc0 .Lstag4_done
	s_sleep 127
	s_sleep 127
	s_sleep 127
